# XOR-swizzled 128B-row LDS layout in P2 big GEMM (conflict-free ds_read_b128)
# speedup vs baseline: 1.0112x; 1.0112x over previous
.LBB0_463:
	s_or_b64 exec, exec, s[14:15]
	s_mov_b64 s[6:7], s[60:61]
	s_waitcnt lgkmcnt(0)
	s_barrier
	s_load_dwordx2 s[16:17], s[6:7], 0x130
	v_mov_b32_e32 v2, v172
	s_mov_b32 s11, s42
	s_mov_b32 s20, s94
	s_waitcnt lgkmcnt(0)
	s_add_u32 s14, s16, 0x6035800
	s_addc_u32 s15, s17, 0
	s_add_u32 s18, s16, 0x3200000
	s_addc_u32 s19, s17, 0
	s_cmpk_lt_i32 s20, 0x600
	s_cbranch_scc0 .LBB0_468
	v_ashrrev_i32_e32 v204, 3, v2
	v_bfe_u32 v3, v2, 4, 2
	v_and_b32_e32 v4, 15, v2
	v_lshlrev_b32_e32 v0, 4, v2
	v_ashrrev_i32_e32 v5, 1, v2
	s_movk_i32 s2, 0xffc0
	v_lshlrev_b32_e32 v2, 1, v2
	v_and_b32_e32 v0, 0x70, v0
	v_and_or_b32 v205, v5, s2, v4
	v_and_b32_e32 v207, 0x80, v2
	s_movk_i32 s2, 0x90
	v_or_b32_e32 v2, v207, v4
	v_and_b32_e32 v5, 7, v204
	v_lshlrev_b32_e32 v5, 4, v5
	v_xor_b32_e32 v5, v5, v0
	v_lshl_add_u32 v166, v204, 7, v5
	v_lshl_add_u64 v[162:163], s[18:19], 0, v[0:1]
	v_lshl_add_u64 v[164:165], s[16:17], 0, v[0:1]
	v_and_b32_e32 v5, 7, v4
	v_xor_b32_e32 v5, v5, v3
	v_lshlrev_b32_e32 v206, 4, v5
	v_lshlrev_b32_e32 v208, 2, v3
	v_lshlrev_b32_e32 v0, 7, v205
	v_lshlrev_b32_e32 v167, 7, v2
.LBB0_465:
	s_mul_hi_i32 s4, s20, 0x38e38e39
	s_lshr_b32 s6, s4, 31
	s_ashr_i32 s4, s4, 4
	s_add_i32 s4, s4, s6
	s_mul_i32 s6, s4, 0x48
	s_sub_i32 s6, s20, s6
	s_lshl_b32 s6, s6, 8
	v_add_u32_e32 v2, s6, v204
	v_ashrrev_i32_e32 v3, 31, v2
	v_lshlrev_b64 v[2:3], 11, v[2:3]
	v_lshl_add_u64 v[168:169], v[162:163], 0, v[2:3]
	v_add_co_u32_e32 v56, vcc, s34, v168
	s_lshl_b32 s7, s4, 8
	s_nop 0
	v_addc_co_u32_e32 v57, vcc, 0, v169, vcc
	v_add_u32_e32 v2, s7, v204
	s_waitcnt vmcnt(9)
	v_add_co_u32_e32 v58, vcc, s35, v168
	v_ashrrev_i32_e32 v3, 31, v2
	s_nop 0
	v_addc_co_u32_e32 v59, vcc, 0, v169, vcc
	v_lshlrev_b64 v[2:3], 11, v[2:3]
	v_add_co_u32_e32 v60, vcc, s36, v168
	v_lshl_add_u64 v[170:171], v[164:165], 0, v[2:3]
	s_nop 0
	v_addc_co_u32_e32 v61, vcc, 0, v169, vcc
	s_waitcnt vmcnt(8)
	v_add_co_u32_e32 v62, vcc, s35, v170
	global_load_dwordx4 v[24:27], v[56:57], off
	global_load_dwordx4 v[28:31], v[58:59], off
	v_addc_co_u32_e32 v63, vcc, 0, v171, vcc
	v_add_co_u32_e32 v64, vcc, s36, v170
	global_load_dwordx4 v[32:35], v[168:169], off
	global_load_dwordx4 v[36:39], v[170:171], off
	v_addc_co_u32_e32 v65, vcc, 0, v171, vcc
	v_add_co_u32_e32 v66, vcc, s34, v170
	global_load_dwordx4 v[40:43], v[62:63], off
	global_load_dwordx4 v[44:47], v[64:65], off
	v_addc_co_u32_e32 v67, vcc, 0, v171, vcc
	global_load_dwordx4 v[48:51], v[60:61], off
	global_load_dwordx4 v[52:55], v[66:67], off
	s_barrier
	global_load_dwordx4 v[106:109], v[56:57], off offset:128
	global_load_dwordx4 v[110:113], v[58:59], off offset:128
	global_load_dwordx4 v[114:117], v[168:169], off offset:128
	global_load_dwordx4 v[122:125], v[170:171], off offset:128
	global_load_dwordx4 v[126:129], v[60:61], off offset:128
	global_load_dwordx4 v[118:121], v[66:67], off offset:128
	global_load_dwordx4 v[134:137], v[62:63], off offset:128
	global_load_dwordx4 v[130:133], v[64:65], off offset:128
	v_mov_b32_e32 v2, 0
	s_mov_b32 s4, 0
	v_mov_b32_e32 v3, v2
	v_mov_b32_e32 v4, v2
	v_mov_b32_e32 v5, v2
	v_mov_b32_e32 v6, v2
	v_mov_b32_e32 v7, v2
	v_mov_b32_e32 v8, v2
	v_mov_b32_e32 v9, v2
	v_mov_b32_e32 v10, v2
	v_mov_b32_e32 v11, v2
	v_mov_b32_e32 v12, v2
	v_mov_b32_e32 v13, v2
	v_mov_b32_e32 v14, v2
	v_mov_b32_e32 v15, v2
	v_mov_b32_e32 v16, v2
	v_mov_b32_e32 v17, v2
	v_mov_b32_e32 v18, v2
	v_mov_b32_e32 v19, v2
	v_mov_b32_e32 v20, v2
	v_mov_b32_e32 v21, v2
	v_mov_b32_e32 v22, v2
	v_mov_b32_e32 v23, v2
	v_mov_b32_e32 v56, v2
	v_mov_b32_e32 v57, v2
	v_mov_b32_e32 v58, v2
	v_mov_b32_e32 v59, v2
	v_mov_b32_e32 v60, v2
	v_mov_b32_e32 v61, v2
	v_mov_b32_e32 v62, v2
	v_mov_b32_e32 v63, v2
	v_mov_b32_e32 v64, v2
	v_mov_b32_e32 v65, v2
	v_mov_b32_e32 v66, v2
	v_mov_b32_e32 v67, v2
	v_mov_b32_e32 v68, v2
	v_mov_b32_e32 v69, v2
	v_mov_b32_e32 v70, v2
	v_mov_b32_e32 v71, v2
	v_mov_b32_e32 v72, v2
	v_mov_b32_e32 v73, v2
	v_mov_b32_e32 v74, v2
	v_mov_b32_e32 v75, v2
	v_mov_b32_e32 v76, v2
	v_mov_b32_e32 v77, v2
	v_mov_b32_e32 v78, v2
	v_mov_b32_e32 v79, v2
	v_mov_b32_e32 v80, v2
	v_mov_b32_e32 v81, v2
	v_mov_b32_e32 v82, v2
	v_mov_b32_e32 v83, v2
	v_mov_b32_e32 v84, v2
	v_mov_b32_e32 v85, v2
	s_waitcnt vmcnt(11)
	ds_write_b128 v166, v[40:43] offset:49152
	s_waitcnt vmcnt(10)
	ds_write_b128 v166, v[44:47] offset:57344
	ds_write_b128 v166, v[32:35]
	ds_write_b128 v166, v[36:39] offset:32768
	ds_write_b128 v166, v[24:27] offset:8192
	ds_write_b128 v166, v[28:31] offset:16384
	s_waitcnt vmcnt(9)
	ds_write_b128 v166, v[48:51] offset:24576
	s_waitcnt vmcnt(8)
	ds_write_b128 v166, v[52:55] offset:40960
	v_mov_b32_e32 v24, v2
	v_mov_b32_e32 v25, v2
	v_mov_b32_e32 v26, v2
	v_mov_b32_e32 v27, v2
	v_mov_b32_e32 v28, v2
	v_mov_b32_e32 v29, v2
	v_mov_b32_e32 v30, v2
	v_mov_b32_e32 v31, v2
	v_mov_b32_e32 v32, v2
	v_mov_b32_e32 v33, v2
	v_mov_b32_e32 v34, v2
	v_mov_b32_e32 v35, v2
	v_mov_b32_e32 v36, v2
	v_mov_b32_e32 v37, v2
	v_mov_b32_e32 v38, v2
	v_mov_b32_e32 v39, v2
	v_mov_b32_e32 v40, v2
	v_mov_b32_e32 v41, v2
	v_mov_b32_e32 v42, v2
	v_mov_b32_e32 v43, v2
	v_mov_b32_e32 v44, v2
	v_mov_b32_e32 v45, v2
	v_mov_b32_e32 v46, v2
	v_mov_b32_e32 v47, v2
	v_mov_b32_e32 v48, v2
	v_mov_b32_e32 v49, v2
	v_mov_b32_e32 v50, v2
	v_mov_b32_e32 v51, v2
	v_mov_b32_e32 v52, v2
	v_mov_b32_e32 v53, v2
	v_mov_b32_e32 v54, v2
	v_mov_b32_e32 v55, v2
	v_mov_b32_e32 v86, v2
	v_mov_b32_e32 v87, v2
	v_mov_b32_e32 v88, v2
	v_mov_b32_e32 v89, v2
	v_mov_b32_e32 v90, v2
	v_mov_b32_e32 v91, v2
	v_mov_b32_e32 v92, v2
	v_mov_b32_e32 v93, v2
	v_mov_b32_e32 v94, v2
	v_mov_b32_e32 v95, v2
	v_mov_b32_e32 v96, v2
	v_mov_b32_e32 v97, v2
	v_mov_b32_e32 v98, v2
	v_mov_b32_e32 v99, v2
	v_mov_b32_e32 v100, v2
	v_mov_b32_e32 v101, v2
	v_mov_b32_e32 v102, v2
	v_mov_b32_e32 v103, v2
	v_mov_b32_e32 v104, v2
	v_mov_b32_e32 v105, v2
	v_mov_b32_e32 v138, v2
	v_mov_b32_e32 v139, v2
	v_mov_b32_e32 v140, v2
	v_mov_b32_e32 v141, v2
	v_mov_b32_e32 v142, v2
	v_mov_b32_e32 v143, v2
	v_mov_b32_e32 v144, v2
	v_mov_b32_e32 v145, v2
	v_mov_b32_e32 v146, v2
	v_mov_b32_e32 v147, v2
	v_mov_b32_e32 v148, v2
	v_mov_b32_e32 v149, v2
	v_mov_b32_e32 v150, v2
	v_mov_b32_e32 v151, v2
	v_mov_b32_e32 v152, v2
	v_mov_b32_e32 v153, v2
	v_mov_b32_e32 v154, v2
	v_mov_b32_e32 v155, v2
	v_mov_b32_e32 v156, v2
	v_mov_b32_e32 v157, v2
	v_mov_b32_e32 v158, v2
	v_mov_b32_e32 v159, v2
	v_mov_b32_e32 v160, v2
	v_mov_b32_e32 v161, v2
	s_waitcnt lgkmcnt(0)
	s_barrier
.LBB0_466:
	s_bitcmp1_b32 s4, 0
	s_cselect_b32 s21, 0x12000, 0
	v_or_b32_e32 v184, s21, v206
	v_add_u32_e32 v185, v184, v0
	v_add_u32_e32 v184, v184, v167
	ds_read_b128 v[210:213], v185
	ds_read_b128 v[214:217], v185 offset:2048
	ds_read_b128 v[218:221], v185 offset:4096
	ds_read_b128 v[222:225], v185 offset:6144
	ds_read_b128 v[226:229], v184 offset:32768
	ds_read_b128 v[230:233], v184 offset:34816
	ds_read_b128 v[234:237], v184 offset:36864
	ds_read_b128 v[238:241], v184 offset:38912
	ds_read_b128 v[242:245], v184 offset:40960
	ds_read_b128 v[246:249], v184 offset:43008
	ds_read_b128 v[198:201], v184 offset:45056
	ds_read_b128 v[184:187], v184 offset:47104
	s_add_i32 s10, s4, 1
	s_bitcmp1_b32 s10, 0
	s_cselect_b32 s23, 0x12000, 0
	s_waitcnt lgkmcnt(7)
	v_mfma_f32_16x16x32_bf16 v[158:161], v[226:229], v[210:213], v[158:161]
	v_mfma_f32_16x16x32_bf16 v[94:97], v[226:229], v[214:217], v[94:97]
	v_mfma_f32_16x16x32_bf16 v[62:65], v[226:229], v[218:221], v[62:65]
	v_mfma_f32_16x16x32_bf16 v[30:33], v[226:229], v[222:225], v[30:33]
	v_add_u32_e32 v226, s23, v166
	s_waitcnt vmcnt(5)
	ds_write_b128 v226, v[114:117]
	s_waitcnt lgkmcnt(7)
	v_mfma_f32_16x16x32_bf16 v[154:157], v[230:233], v[210:213], v[154:157]
	v_mfma_f32_16x16x32_bf16 v[90:93], v[230:233], v[214:217], v[90:93]
	v_mfma_f32_16x16x32_bf16 v[58:61], v[230:233], v[218:221], v[58:61]
	v_mfma_f32_16x16x32_bf16 v[26:29], v[230:233], v[222:225], v[26:29]
	ds_write_b128 v226, v[106:109] offset:8192
	s_waitcnt lgkmcnt(7)
	v_mfma_f32_16x16x32_bf16 v[150:153], v[234:237], v[210:213], v[150:153]
	v_mfma_f32_16x16x32_bf16 v[86:89], v[234:237], v[214:217], v[86:89]
	v_mfma_f32_16x16x32_bf16 v[54:57], v[234:237], v[218:221], v[54:57]
	v_mfma_f32_16x16x32_bf16 v[22:25], v[234:237], v[222:225], v[22:25]
	ds_write_b128 v226, v[110:113] offset:16384
	s_waitcnt lgkmcnt(7)
	v_mfma_f32_16x16x32_bf16 v[146:149], v[238:241], v[210:213], v[146:149]
	v_mfma_f32_16x16x32_bf16 v[82:85], v[238:241], v[214:217], v[82:85]
	v_mfma_f32_16x16x32_bf16 v[50:53], v[238:241], v[218:221], v[50:53]
	v_mfma_f32_16x16x32_bf16 v[18:21], v[238:241], v[222:225], v[18:21]
	s_waitcnt vmcnt(3)
	ds_write_b128 v226, v[126:129] offset:24576
	s_waitcnt lgkmcnt(7)
	v_mfma_f32_16x16x32_bf16 v[142:145], v[242:245], v[210:213], v[142:145]
	v_mfma_f32_16x16x32_bf16 v[78:81], v[242:245], v[214:217], v[78:81]
	v_mfma_f32_16x16x32_bf16 v[46:49], v[242:245], v[218:221], v[46:49]
	v_mfma_f32_16x16x32_bf16 v[14:17], v[242:245], v[222:225], v[14:17]
	ds_write_b128 v226, v[122:125] offset:32768
	s_waitcnt lgkmcnt(7)
	v_mfma_f32_16x16x32_bf16 v[138:141], v[246:249], v[210:213], v[138:141]
	v_mfma_f32_16x16x32_bf16 v[74:77], v[246:249], v[214:217], v[74:77]
	v_mfma_f32_16x16x32_bf16 v[42:45], v[246:249], v[218:221], v[42:45]
	v_mfma_f32_16x16x32_bf16 v[10:13], v[246:249], v[222:225], v[10:13]
	s_waitcnt vmcnt(2)
	ds_write_b128 v226, v[118:121] offset:40960
	s_waitcnt lgkmcnt(7)
	v_mfma_f32_16x16x32_bf16 v[102:105], v[198:201], v[210:213], v[102:105]
	v_mfma_f32_16x16x32_bf16 v[70:73], v[198:201], v[214:217], v[70:73]
	v_mfma_f32_16x16x32_bf16 v[38:41], v[198:201], v[218:221], v[38:41]
	v_mfma_f32_16x16x32_bf16 v[6:9], v[198:201], v[222:225], v[6:9]
	s_waitcnt vmcnt(1)
	ds_write_b128 v226, v[134:137] offset:49152
	s_waitcnt lgkmcnt(7)
	v_mfma_f32_16x16x32_bf16 v[98:101], v[184:187], v[210:213], v[98:101]
	v_mfma_f32_16x16x32_bf16 v[66:69], v[184:187], v[214:217], v[66:69]
	v_mfma_f32_16x16x32_bf16 v[34:37], v[184:187], v[218:221], v[34:37]
	v_mfma_f32_16x16x32_bf16 v[2:5], v[184:187], v[222:225], v[2:5]
	s_waitcnt vmcnt(0)
	ds_write_b128 v226, v[130:133] offset:57344
	s_min_i32 s4, s4, 13
	s_lshl_b32 s4, s4, 7
	v_lshl_add_u64 v[110:111], v[168:169], 0, s[4:5]
	v_add_co_u32_e32 v106, vcc, s34, v110
	v_lshl_add_u64 v[130:131], v[170:171], 0, s[4:5]
	s_nop 0
	v_addc_co_u32_e32 v107, vcc, 0, v111, vcc
	v_add_co_u32_e32 v112, vcc, s35, v110
	global_load_dwordx4 v[114:117], v[110:111], off offset:256
	s_nop 0
	v_addc_co_u32_e32 v113, vcc, 0, v111, vcc
	v_add_co_u32_e32 v118, vcc, s36, v110
	global_load_dwordx4 v[106:109], v[106:107], off offset:256
	s_nop 0
	v_addc_co_u32_e32 v119, vcc, 0, v111, vcc
	global_load_dwordx4 v[110:113], v[112:113], off offset:256
	v_add3_u32 v214, s21, v0, v206
	v_xor_b32_e32 v214, 64, v214
	global_load_dwordx4 v[126:129], v[118:119], off offset:256
	v_add_co_u32_e32 v118, vcc, s34, v130
	global_load_dwordx4 v[122:125], v[130:131], off offset:256
	s_nop 0
	v_addc_co_u32_e32 v119, vcc, 0, v131, vcc
	v_add_co_u32_e32 v132, vcc, s35, v130
	global_load_dwordx4 v[118:121], v[118:119], off offset:256
	s_nop 0
	v_addc_co_u32_e32 v133, vcc, 0, v131, vcc
	v_add_co_u32_e32 v130, vcc, s36, v130
	global_load_dwordx4 v[134:137], v[132:133], off offset:256
	s_nop 0
	v_addc_co_u32_e32 v131, vcc, 0, v131, vcc
	global_load_dwordx4 v[130:133], v[130:131], off offset:256
	v_add3_u32 v246, s21, v167, v206
	v_xor_b32_e32 v246, 64, v246
	ds_read_b128 v[184:187], v214
	ds_read_b128 v[198:201], v214 offset:2048
	ds_read_b128 v[210:213], v214 offset:4096
	ds_read_b128 v[218:221], v246 offset:32768
	ds_read_b128 v[214:217], v214 offset:6144
	ds_read_b128 v[222:225], v246 offset:34816
	ds_read_b128 v[226:229], v246 offset:36864
	ds_read_b128 v[230:233], v246 offset:38912
	ds_read_b128 v[234:237], v246 offset:40960
	ds_read_b128 v[238:241], v246 offset:43008
	ds_read_b128 v[242:245], v246 offset:45056
	ds_read_b128 v[246:249], v246 offset:47104
	s_waitcnt lgkmcnt(8)
	v_mfma_f32_16x16x32_bf16 v[158:161], v[218:221], v[184:187], v[158:161]
	v_mfma_f32_16x16x32_bf16 v[94:97], v[218:221], v[198:201], v[94:97]
	v_mfma_f32_16x16x32_bf16 v[62:65], v[218:221], v[210:213], v[62:65]
	s_waitcnt lgkmcnt(7)
	v_mfma_f32_16x16x32_bf16 v[30:33], v[218:221], v[214:217], v[30:33]
	s_waitcnt lgkmcnt(6)
	v_mfma_f32_16x16x32_bf16 v[154:157], v[222:225], v[184:187], v[154:157]
	v_mfma_f32_16x16x32_bf16 v[90:93], v[222:225], v[198:201], v[90:93]
	v_mfma_f32_16x16x32_bf16 v[58:61], v[222:225], v[210:213], v[58:61]
	v_mfma_f32_16x16x32_bf16 v[26:29], v[222:225], v[214:217], v[26:29]
	s_waitcnt lgkmcnt(5)
	v_mfma_f32_16x16x32_bf16 v[150:153], v[226:229], v[184:187], v[150:153]
	v_mfma_f32_16x16x32_bf16 v[86:89], v[226:229], v[198:201], v[86:89]
	v_mfma_f32_16x16x32_bf16 v[54:57], v[226:229], v[210:213], v[54:57]
	v_mfma_f32_16x16x32_bf16 v[22:25], v[226:229], v[214:217], v[22:25]
	s_waitcnt lgkmcnt(4)
	v_mfma_f32_16x16x32_bf16 v[146:149], v[230:233], v[184:187], v[146:149]
	v_mfma_f32_16x16x32_bf16 v[82:85], v[230:233], v[198:201], v[82:85]
	v_mfma_f32_16x16x32_bf16 v[50:53], v[230:233], v[210:213], v[50:53]
	v_mfma_f32_16x16x32_bf16 v[18:21], v[230:233], v[214:217], v[18:21]
	s_waitcnt lgkmcnt(3)
	v_mfma_f32_16x16x32_bf16 v[142:145], v[234:237], v[184:187], v[142:145]
	v_mfma_f32_16x16x32_bf16 v[78:81], v[234:237], v[198:201], v[78:81]
	v_mfma_f32_16x16x32_bf16 v[46:49], v[234:237], v[210:213], v[46:49]
	v_mfma_f32_16x16x32_bf16 v[14:17], v[234:237], v[214:217], v[14:17]
	s_waitcnt lgkmcnt(2)
	v_mfma_f32_16x16x32_bf16 v[138:141], v[238:241], v[184:187], v[138:141]
	v_mfma_f32_16x16x32_bf16 v[74:77], v[238:241], v[198:201], v[74:77]
	v_mfma_f32_16x16x32_bf16 v[42:45], v[238:241], v[210:213], v[42:45]
	v_mfma_f32_16x16x32_bf16 v[10:13], v[238:241], v[214:217], v[10:13]
	s_waitcnt lgkmcnt(1)
	v_mfma_f32_16x16x32_bf16 v[102:105], v[242:245], v[184:187], v[102:105]
	v_mfma_f32_16x16x32_bf16 v[70:73], v[242:245], v[198:201], v[70:73]
	v_mfma_f32_16x16x32_bf16 v[38:41], v[242:245], v[210:213], v[38:41]
	v_mfma_f32_16x16x32_bf16 v[6:9], v[242:245], v[214:217], v[6:9]
	s_waitcnt lgkmcnt(0)
	v_mfma_f32_16x16x32_bf16 v[98:101], v[246:249], v[184:187], v[98:101]
	v_mfma_f32_16x16x32_bf16 v[66:69], v[246:249], v[198:201], v[66:69]
	v_mfma_f32_16x16x32_bf16 v[34:37], v[246:249], v[210:213], v[34:37]
	v_mfma_f32_16x16x32_bf16 v[2:5], v[246:249], v[214:217], v[2:5]
	s_waitcnt lgkmcnt(0)
	s_barrier
	s_cmp_eq_u32 s10, 16
	s_mov_b32 s4, s10
	s_cbranch_scc0 .LBB0_466
	s_waitcnt vmcnt(6)
	v_mul_f32_e32 v109, 0xbfb8aa3b, v158
	v_exp_f32_e32 v109, v109
	s_waitcnt vmcnt(5)
	v_mul_f32_e32 v111, 0xbfb8aa3b, v159
	v_exp_f32_e32 v111, v111
	v_mul_f32_e32 v115, 0xbfb8aa3b, v161
	v_add_f32_e32 v109, 1.0, v109
	v_rcp_f32_e32 v114, v109
	v_add_f32_e32 v109, 1.0, v111
	v_mul_f32_e32 v111, 0xbfb8aa3b, v160
	v_exp_f32_e32 v111, v111
	v_exp_f32_e32 v117, v115
	v_rcp_f32_e32 v116, v109
	s_waitcnt vmcnt(2)
	v_mov_b32_e32 v118, v158
	v_add_f32_e32 v109, 1.0, v111
	v_rcp_f32_e32 v115, v109
	v_add_f32_e32 v109, 1.0, v117
	v_rcp_f32_e32 v117, v109
	v_mov_b32_e32 v119, v160
	v_pk_mul_f32 v[114:115], v[118:119], v[114:115]
	v_mov_b32_e32 v118, v154
	v_mov_b32_e32 v119, v156
	v_mov_b32_e32 v160, v159
	v_pk_mul_f32 v[114:115], v[118:119], v[114:115]
	v_pk_mul_f32 v[116:117], v[160:161], v[116:117]
	v_mov_b32_e32 v156, v155
	v_pk_mul_f32 v[116:117], v[156:157], v[116:117]
	v_and_b32_sdwa v111, v115, v177 dst_sel:DWORD dst_unused:UNUSED_PAD src0_sel:WORD_1 src1_sel:DWORD
	v_and_b32_sdwa v118, v114, v177 dst_sel:DWORD dst_unused:UNUSED_PAD src0_sel:WORD_1 src1_sel:DWORD
	v_add3_u32 v111, v115, v111, s28
	v_and_b32_sdwa v115, v117, v177 dst_sel:DWORD dst_unused:UNUSED_PAD src0_sel:WORD_1 src1_sel:DWORD
	v_add3_u32 v114, v114, v118, s28
	v_and_b32_sdwa v118, v116, v177 dst_sel:DWORD dst_unused:UNUSED_PAD src0_sel:WORD_1 src1_sel:DWORD
	v_add3_u32 v115, v117, v115, s28
	v_or_b32_e32 v106, s7, v207
	v_add3_u32 v116, v116, v118, s28
	v_and_b32_e32 v115, 0xffff0000, v115
	v_ashrrev_i32_e32 v106, 1, v106
	v_and_b32_e32 v116, 0xffff0000, v116
	v_or_b32_sdwa v115, v115, v111 dst_sel:DWORD dst_unused:UNUSED_PAD src0_sel:DWORD src1_sel:WORD_1
	v_mul_f32_e32 v111, 0xbfb8aa3b, v150
	v_or_b32_e32 v108, v106, v208
	v_or_b32_sdwa v114, v116, v114 dst_sel:DWORD dst_unused:UNUSED_PAD src0_sel:DWORD src1_sel:WORD_1
	v_exp_f32_e32 v111, v111
	v_mul_f32_e32 v116, 0xbfb8aa3b, v151
	v_add_u32_e32 v110, s6, v205
	v_mov_b64_e32 v[106:107], s[14:15]
	v_ashrrev_i32_e32 v109, 31, v108
	v_exp_f32_e32 v116, v116
	v_mad_i64_i32 v[112:113], s[6:7], v110, s52, v[106:107]
	v_lshlrev_b64 v[108:109], 1, v[108:109]
	v_lshl_add_u64 v[112:113], v[112:113], 0, v[108:109]
	s_waitcnt vmcnt(0)
	global_store_dwordx2 v[112:113], v[114:115], off
	v_add_f32_e32 v111, 1.0, v111
	v_mul_f32_e32 v115, 0xbfb8aa3b, v152
	v_rcp_f32_e32 v114, v111
	v_add_f32_e32 v111, 1.0, v116
	v_exp_f32_e32 v115, v115
	v_mul_f32_e32 v116, 0xbfb8aa3b, v153
	v_exp_f32_e32 v117, v116
	v_rcp_f32_e32 v116, v111
	v_add_f32_e32 v111, 1.0, v115
	v_rcp_f32_e32 v115, v111
	v_add_f32_e32 v111, 1.0, v117
	v_rcp_f32_e32 v117, v111
	v_mov_b32_e32 v118, v150
	v_mov_b32_e32 v119, v152
	v_pk_mul_f32 v[114:115], v[118:119], v[114:115]
	v_mov_b32_e32 v118, v146
	v_mov_b32_e32 v119, v148
	v_mov_b32_e32 v152, v151
	v_pk_mul_f32 v[114:115], v[118:119], v[114:115]
	v_pk_mul_f32 v[116:117], v[152:153], v[116:117]
	v_mov_b32_e32 v148, v147
	v_pk_mul_f32 v[116:117], v[148:149], v[116:117]
	v_and_b32_sdwa v111, v115, v177 dst_sel:DWORD dst_unused:UNUSED_PAD src0_sel:WORD_1 src1_sel:DWORD
	v_and_b32_sdwa v118, v114, v177 dst_sel:DWORD dst_unused:UNUSED_PAD src0_sel:WORD_1 src1_sel:DWORD
	v_add3_u32 v111, v115, v111, s28
	v_and_b32_sdwa v115, v117, v177 dst_sel:DWORD dst_unused:UNUSED_PAD src0_sel:WORD_1 src1_sel:DWORD
	v_add3_u32 v114, v114, v118, s28
	v_and_b32_sdwa v118, v116, v177 dst_sel:DWORD dst_unused:UNUSED_PAD src0_sel:WORD_1 src1_sel:DWORD
	v_add3_u32 v115, v117, v115, s28
	v_add3_u32 v116, v116, v118, s28
	v_and_b32_e32 v115, 0xffff0000, v115
	v_and_b32_e32 v116, 0xffff0000, v116
	v_or_b32_sdwa v115, v115, v111 dst_sel:DWORD dst_unused:UNUSED_PAD src0_sel:DWORD src1_sel:WORD_1
	v_mul_f32_e32 v111, 0xbfb8aa3b, v142
	v_or_b32_sdwa v114, v116, v114 dst_sel:DWORD dst_unused:UNUSED_PAD src0_sel:DWORD src1_sel:WORD_1
	v_exp_f32_e32 v111, v111
	v_mul_f32_e32 v116, 0xbfb8aa3b, v143
	v_exp_f32_e32 v116, v116
	global_store_dwordx2 v[112:113], v[114:115], off offset:32
	v_add_f32_e32 v111, 1.0, v111
	v_mul_f32_e32 v115, 0xbfb8aa3b, v144
	v_rcp_f32_e32 v114, v111
	v_add_f32_e32 v111, 1.0, v116
	v_exp_f32_e32 v115, v115
	v_mul_f32_e32 v116, 0xbfb8aa3b, v145
	v_exp_f32_e32 v117, v116
	v_rcp_f32_e32 v116, v111
	v_add_f32_e32 v111, 1.0, v115
	v_rcp_f32_e32 v115, v111
	v_add_f32_e32 v111, 1.0, v117
	v_rcp_f32_e32 v117, v111
	v_mov_b32_e32 v118, v142
	v_mov_b32_e32 v119, v144
	v_pk_mul_f32 v[114:115], v[118:119], v[114:115]
	v_mov_b32_e32 v118, v138
	v_mov_b32_e32 v119, v140
	v_mov_b32_e32 v144, v143
	v_pk_mul_f32 v[114:115], v[118:119], v[114:115]
	v_pk_mul_f32 v[116:117], v[144:145], v[116:117]
	v_mov_b32_e32 v140, v139
	v_pk_mul_f32 v[116:117], v[140:141], v[116:117]
	v_and_b32_sdwa v111, v115, v177 dst_sel:DWORD dst_unused:UNUSED_PAD src0_sel:WORD_1 src1_sel:DWORD
	v_and_b32_sdwa v118, v114, v177 dst_sel:DWORD dst_unused:UNUSED_PAD src0_sel:WORD_1 src1_sel:DWORD
	v_add3_u32 v111, v115, v111, s28
	v_and_b32_sdwa v115, v117, v177 dst_sel:DWORD dst_unused:UNUSED_PAD src0_sel:WORD_1 src1_sel:DWORD
	v_add3_u32 v114, v114, v118, s28
	v_and_b32_sdwa v118, v116, v177 dst_sel:DWORD dst_unused:UNUSED_PAD src0_sel:WORD_1 src1_sel:DWORD
	v_add3_u32 v115, v117, v115, s28
	v_add3_u32 v116, v116, v118, s28
	v_and_b32_e32 v115, 0xffff0000, v115
	v_and_b32_e32 v116, 0xffff0000, v116
	v_or_b32_sdwa v115, v115, v111 dst_sel:DWORD dst_unused:UNUSED_PAD src0_sel:DWORD src1_sel:WORD_1
	v_mul_f32_e32 v111, 0xbfb8aa3b, v102
	v_or_b32_sdwa v114, v116, v114 dst_sel:DWORD dst_unused:UNUSED_PAD src0_sel:DWORD src1_sel:WORD_1
	v_exp_f32_e32 v111, v111
	v_mul_f32_e32 v116, 0xbfb8aa3b, v103
	v_exp_f32_e32 v116, v116
	global_store_dwordx2 v[112:113], v[114:115], off offset:64
	v_add_f32_e32 v111, 1.0, v111
	v_mul_f32_e32 v115, 0xbfb8aa3b, v104
	v_rcp_f32_e32 v114, v111
	v_add_f32_e32 v111, 1.0, v116
	v_exp_f32_e32 v115, v115
	v_mul_f32_e32 v116, 0xbfb8aa3b, v105
	v_exp_f32_e32 v117, v116
	v_rcp_f32_e32 v116, v111
	v_add_f32_e32 v111, 1.0, v115
	v_rcp_f32_e32 v115, v111
	v_add_f32_e32 v111, 1.0, v117
	v_rcp_f32_e32 v117, v111
	v_mov_b32_e32 v118, v102
	v_mov_b32_e32 v119, v104
	v_mov_b32_e32 v104, v103
	v_pk_mul_f32 v[114:115], v[118:119], v[114:115]
	v_mov_b32_e32 v119, v100
	v_pk_mul_f32 v[102:103], v[104:105], v[116:117]
	v_mov_b32_e32 v100, v99
	v_mov_b32_e32 v118, v98
	v_pk_mul_f32 v[98:99], v[100:101], v[102:103]
	v_pk_mul_f32 v[114:115], v[118:119], v[114:115]
	v_and_b32_sdwa v102, v99, v177 dst_sel:DWORD dst_unused:UNUSED_PAD src0_sel:WORD_1 src1_sel:DWORD
	v_and_b32_sdwa v103, v98, v177 dst_sel:DWORD dst_unused:UNUSED_PAD src0_sel:WORD_1 src1_sel:DWORD
	v_and_b32_sdwa v100, v115, v177 dst_sel:DWORD dst_unused:UNUSED_PAD src0_sel:WORD_1 src1_sel:DWORD
	v_and_b32_sdwa v101, v114, v177 dst_sel:DWORD dst_unused:UNUSED_PAD src0_sel:WORD_1 src1_sel:DWORD
	v_add3_u32 v99, v99, v102, s28
	v_add3_u32 v98, v98, v103, s28
	v_add3_u32 v101, v114, v101, s28
	v_add3_u32 v100, v115, v100, s28
	v_and_b32_e32 v99, 0xffff0000, v99
	v_and_b32_e32 v98, 0xffff0000, v98
	v_or_b32_sdwa v99, v99, v100 dst_sel:DWORD dst_unused:UNUSED_PAD src0_sel:DWORD src1_sel:WORD_1
	v_or_b32_sdwa v98, v98, v101 dst_sel:DWORD dst_unused:UNUSED_PAD src0_sel:DWORD src1_sel:WORD_1
	global_store_dwordx2 v[112:113], v[98:99], off offset:96
	v_mul_f32_e32 v99, 0xbfb8aa3b, v94
	v_exp_f32_e32 v100, v99
	v_mul_f32_e32 v99, 0xbfb8aa3b, v95
	v_mul_f32_e32 v102, 0xbfb8aa3b, v96
	v_exp_f32_e32 v101, v99
	v_exp_f32_e32 v103, v102
	v_mul_f32_e32 v102, 0xbfb8aa3b, v97
	v_exp_f32_e32 v104, v102
	v_add_f32_e32 v101, 1.0, v101
	v_add_f32_e32 v100, 1.0, v100
	v_rcp_f32_e32 v102, v101
	v_add_f32_e32 v101, 1.0, v103
	v_add_f32_e32 v103, 1.0, v104
	v_rcp_f32_e32 v100, v100
	v_rcp_f32_e32 v101, v101
	v_rcp_f32_e32 v103, v103
	v_mov_b32_e32 v104, v94
	v_mov_b32_e32 v105, v96
	v_mov_b32_e32 v96, v95
	v_pk_mul_f32 v[100:101], v[104:105], v[100:101]
	v_mov_b32_e32 v105, v92
	v_pk_mul_f32 v[94:95], v[96:97], v[102:103]
	v_mov_b32_e32 v92, v91
	v_mov_b32_e32 v104, v90
	v_pk_mul_f32 v[90:91], v[92:93], v[94:95]
	v_pk_mul_f32 v[100:101], v[104:105], v[100:101]
	v_and_b32_sdwa v94, v91, v177 dst_sel:DWORD dst_unused:UNUSED_PAD src0_sel:WORD_1 src1_sel:DWORD
	v_and_b32_sdwa v92, v101, v177 dst_sel:DWORD dst_unused:UNUSED_PAD src0_sel:WORD_1 src1_sel:DWORD
	v_and_b32_sdwa v95, v90, v177 dst_sel:DWORD dst_unused:UNUSED_PAD src0_sel:WORD_1 src1_sel:DWORD
	v_add3_u32 v91, v91, v94, s28
	v_and_b32_sdwa v93, v100, v177 dst_sel:DWORD dst_unused:UNUSED_PAD src0_sel:WORD_1 src1_sel:DWORD
	v_add3_u32 v92, v101, v92, s28
	v_add3_u32 v90, v90, v95, s28
	v_and_b32_e32 v91, 0xffff0000, v91
	v_add3_u32 v93, v100, v93, s28
	v_and_b32_e32 v90, 0xffff0000, v90
	v_or_b32_sdwa v91, v91, v92 dst_sel:DWORD dst_unused:UNUSED_PAD src0_sel:DWORD src1_sel:WORD_1
	v_mul_f32_e32 v92, 0xbfb8aa3b, v86
	v_or_b32_sdwa v90, v90, v93 dst_sel:DWORD dst_unused:UNUSED_PAD src0_sel:DWORD src1_sel:WORD_1
	v_exp_f32_e32 v92, v92
	v_mul_f32_e32 v93, 0xbfb8aa3b, v87
	v_or_b32_e32 v98, 16, v110
	v_exp_f32_e32 v93, v93
	v_mad_i64_i32 v[98:99], s[6:7], v98, s52, v[106:107]
	v_lshl_add_u64 v[98:99], v[98:99], 0, v[108:109]
	global_store_dwordx2 v[98:99], v[90:91], off
	v_add_f32_e32 v90, 1.0, v92
	v_mul_f32_e32 v92, 0xbfb8aa3b, v88
	v_add_f32_e32 v91, 1.0, v93
	v_exp_f32_e32 v93, v92
	v_mul_f32_e32 v92, 0xbfb8aa3b, v89
	v_exp_f32_e32 v94, v92
	v_rcp_f32_e32 v92, v91
	v_add_f32_e32 v91, 1.0, v93
	v_rcp_f32_e32 v90, v90
	v_add_f32_e32 v93, 1.0, v94
	v_rcp_f32_e32 v91, v91
	v_rcp_f32_e32 v93, v93
	v_mov_b32_e32 v94, v86
	v_mov_b32_e32 v95, v88
	v_mov_b32_e32 v88, v87
	v_pk_mul_f32 v[90:91], v[94:95], v[90:91]
	v_mov_b32_e32 v95, v84
	v_pk_mul_f32 v[86:87], v[88:89], v[92:93]
	v_mov_b32_e32 v84, v83
	v_mov_b32_e32 v94, v82
	v_pk_mul_f32 v[82:83], v[84:85], v[86:87]
	v_pk_mul_f32 v[90:91], v[94:95], v[90:91]
	v_and_b32_sdwa v86, v83, v177 dst_sel:DWORD dst_unused:UNUSED_PAD src0_sel:WORD_1 src1_sel:DWORD
	v_and_b32_sdwa v84, v91, v177 dst_sel:DWORD dst_unused:UNUSED_PAD src0_sel:WORD_1 src1_sel:DWORD
	v_and_b32_sdwa v87, v82, v177 dst_sel:DWORD dst_unused:UNUSED_PAD src0_sel:WORD_1 src1_sel:DWORD
	v_add3_u32 v83, v83, v86, s28
	v_and_b32_sdwa v85, v90, v177 dst_sel:DWORD dst_unused:UNUSED_PAD src0_sel:WORD_1 src1_sel:DWORD
	v_add3_u32 v84, v91, v84, s28
	v_add3_u32 v82, v82, v87, s28
	v_and_b32_e32 v83, 0xffff0000, v83
	v_add3_u32 v85, v90, v85, s28
	v_and_b32_e32 v82, 0xffff0000, v82
	v_or_b32_sdwa v83, v83, v84 dst_sel:DWORD dst_unused:UNUSED_PAD src0_sel:DWORD src1_sel:WORD_1
	v_mul_f32_e32 v84, 0xbfb8aa3b, v78
	v_or_b32_sdwa v82, v82, v85 dst_sel:DWORD dst_unused:UNUSED_PAD src0_sel:DWORD src1_sel:WORD_1
	v_exp_f32_e32 v84, v84
	v_mul_f32_e32 v85, 0xbfb8aa3b, v79
	v_exp_f32_e32 v85, v85
	global_store_dwordx2 v[98:99], v[82:83], off offset:32
	v_add_f32_e32 v82, 1.0, v84
	v_mul_f32_e32 v84, 0xbfb8aa3b, v80
	v_add_f32_e32 v83, 1.0, v85
	v_exp_f32_e32 v85, v84
	v_mul_f32_e32 v84, 0xbfb8aa3b, v81
	v_exp_f32_e32 v86, v84
	v_rcp_f32_e32 v84, v83
	v_add_f32_e32 v83, 1.0, v85
	v_rcp_f32_e32 v82, v82
	v_add_f32_e32 v85, 1.0, v86
	v_rcp_f32_e32 v83, v83
	v_rcp_f32_e32 v85, v85
	v_mov_b32_e32 v86, v78
	v_mov_b32_e32 v87, v80
	v_mov_b32_e32 v80, v79
	v_pk_mul_f32 v[82:83], v[86:87], v[82:83]
	v_mov_b32_e32 v87, v76
	v_pk_mul_f32 v[78:79], v[80:81], v[84:85]
	v_mov_b32_e32 v76, v75
	v_mov_b32_e32 v86, v74
	v_pk_mul_f32 v[74:75], v[76:77], v[78:79]
	v_pk_mul_f32 v[82:83], v[86:87], v[82:83]
	v_and_b32_sdwa v78, v75, v177 dst_sel:DWORD dst_unused:UNUSED_PAD src0_sel:WORD_1 src1_sel:DWORD
	v_and_b32_sdwa v76, v83, v177 dst_sel:DWORD dst_unused:UNUSED_PAD src0_sel:WORD_1 src1_sel:DWORD
	v_and_b32_sdwa v79, v74, v177 dst_sel:DWORD dst_unused:UNUSED_PAD src0_sel:WORD_1 src1_sel:DWORD
	v_add3_u32 v75, v75, v78, s28
	v_and_b32_sdwa v77, v82, v177 dst_sel:DWORD dst_unused:UNUSED_PAD src0_sel:WORD_1 src1_sel:DWORD
	v_add3_u32 v76, v83, v76, s28
	v_add3_u32 v74, v74, v79, s28
	v_and_b32_e32 v75, 0xffff0000, v75
	v_add3_u32 v77, v82, v77, s28
	v_and_b32_e32 v74, 0xffff0000, v74
	v_or_b32_sdwa v75, v75, v76 dst_sel:DWORD dst_unused:UNUSED_PAD src0_sel:DWORD src1_sel:WORD_1
	v_mul_f32_e32 v76, 0xbfb8aa3b, v70
	v_or_b32_sdwa v74, v74, v77 dst_sel:DWORD dst_unused:UNUSED_PAD src0_sel:DWORD src1_sel:WORD_1
	v_exp_f32_e32 v76, v76
	v_mul_f32_e32 v77, 0xbfb8aa3b, v71
	v_exp_f32_e32 v77, v77
	global_store_dwordx2 v[98:99], v[74:75], off offset:64
	v_add_f32_e32 v74, 1.0, v76
	v_mul_f32_e32 v76, 0xbfb8aa3b, v72
	v_add_f32_e32 v75, 1.0, v77
	v_exp_f32_e32 v77, v76
	v_mul_f32_e32 v76, 0xbfb8aa3b, v73
	v_exp_f32_e32 v78, v76
	v_rcp_f32_e32 v76, v75
	v_add_f32_e32 v75, 1.0, v77
	v_rcp_f32_e32 v74, v74
	v_add_f32_e32 v77, 1.0, v78
	v_rcp_f32_e32 v75, v75
	v_rcp_f32_e32 v77, v77
	v_mov_b32_e32 v78, v70
	v_mov_b32_e32 v79, v72
	v_mov_b32_e32 v72, v71
	v_pk_mul_f32 v[74:75], v[78:79], v[74:75]
	v_mov_b32_e32 v79, v68
	v_pk_mul_f32 v[70:71], v[72:73], v[76:77]
	v_mov_b32_e32 v68, v67
	v_mov_b32_e32 v78, v66
	v_pk_mul_f32 v[66:67], v[68:69], v[70:71]
	v_pk_mul_f32 v[74:75], v[78:79], v[74:75]
	v_and_b32_sdwa v70, v67, v177 dst_sel:DWORD dst_unused:UNUSED_PAD src0_sel:WORD_1 src1_sel:DWORD
	v_and_b32_sdwa v71, v66, v177 dst_sel:DWORD dst_unused:UNUSED_PAD src0_sel:WORD_1 src1_sel:DWORD
	v_and_b32_sdwa v68, v75, v177 dst_sel:DWORD dst_unused:UNUSED_PAD src0_sel:WORD_1 src1_sel:DWORD
	v_and_b32_sdwa v69, v74, v177 dst_sel:DWORD dst_unused:UNUSED_PAD src0_sel:WORD_1 src1_sel:DWORD
	v_add3_u32 v67, v67, v70, s28
	v_add3_u32 v66, v66, v71, s28
	v_add3_u32 v69, v74, v69, s28
	v_add3_u32 v68, v75, v68, s28
	v_and_b32_e32 v67, 0xffff0000, v67
	v_and_b32_e32 v66, 0xffff0000, v66
	v_or_b32_sdwa v67, v67, v68 dst_sel:DWORD dst_unused:UNUSED_PAD src0_sel:DWORD src1_sel:WORD_1
	v_or_b32_sdwa v66, v66, v69 dst_sel:DWORD dst_unused:UNUSED_PAD src0_sel:DWORD src1_sel:WORD_1
	global_store_dwordx2 v[98:99], v[66:67], off offset:96
	v_mul_f32_e32 v67, 0xbfb8aa3b, v62
	v_exp_f32_e32 v68, v67
	v_mul_f32_e32 v67, 0xbfb8aa3b, v63
	v_mul_f32_e32 v70, 0xbfb8aa3b, v64
	v_exp_f32_e32 v69, v67
	v_exp_f32_e32 v71, v70
	v_mul_f32_e32 v70, 0xbfb8aa3b, v65
	v_exp_f32_e32 v72, v70
	v_add_f32_e32 v69, 1.0, v69
	v_add_f32_e32 v68, 1.0, v68
	v_rcp_f32_e32 v70, v69
	v_add_f32_e32 v69, 1.0, v71
	v_add_f32_e32 v71, 1.0, v72
	v_rcp_f32_e32 v68, v68
	v_rcp_f32_e32 v69, v69
	v_rcp_f32_e32 v71, v71
	v_mov_b32_e32 v72, v62
	v_mov_b32_e32 v73, v64
	v_mov_b32_e32 v64, v63
	v_pk_mul_f32 v[68:69], v[72:73], v[68:69]
	v_mov_b32_e32 v73, v60
	v_pk_mul_f32 v[62:63], v[64:65], v[70:71]
	v_mov_b32_e32 v60, v59
	v_mov_b32_e32 v72, v58
	v_pk_mul_f32 v[58:59], v[60:61], v[62:63]
	v_pk_mul_f32 v[68:69], v[72:73], v[68:69]
	v_and_b32_sdwa v62, v59, v177 dst_sel:DWORD dst_unused:UNUSED_PAD src0_sel:WORD_1 src1_sel:DWORD
	v_and_b32_sdwa v60, v69, v177 dst_sel:DWORD dst_unused:UNUSED_PAD src0_sel:WORD_1 src1_sel:DWORD
	v_and_b32_sdwa v63, v58, v177 dst_sel:DWORD dst_unused:UNUSED_PAD src0_sel:WORD_1 src1_sel:DWORD
	v_add3_u32 v59, v59, v62, s28
	v_and_b32_sdwa v61, v68, v177 dst_sel:DWORD dst_unused:UNUSED_PAD src0_sel:WORD_1 src1_sel:DWORD
	v_add3_u32 v60, v69, v60, s28
	v_add3_u32 v58, v58, v63, s28
	v_and_b32_e32 v59, 0xffff0000, v59
	v_add3_u32 v61, v68, v61, s28
	v_and_b32_e32 v58, 0xffff0000, v58
	v_or_b32_sdwa v59, v59, v60 dst_sel:DWORD dst_unused:UNUSED_PAD src0_sel:DWORD src1_sel:WORD_1
	v_mul_f32_e32 v60, 0xbfb8aa3b, v54
	v_or_b32_sdwa v58, v58, v61 dst_sel:DWORD dst_unused:UNUSED_PAD src0_sel:DWORD src1_sel:WORD_1
	v_exp_f32_e32 v60, v60
	v_mul_f32_e32 v61, 0xbfb8aa3b, v55
	v_or_b32_e32 v66, 32, v110
	v_exp_f32_e32 v61, v61
	v_mad_i64_i32 v[66:67], s[6:7], v66, s52, v[106:107]
	v_lshl_add_u64 v[66:67], v[66:67], 0, v[108:109]
	global_store_dwordx2 v[66:67], v[58:59], off
	v_add_f32_e32 v58, 1.0, v60
	v_mul_f32_e32 v60, 0xbfb8aa3b, v56
	v_add_f32_e32 v59, 1.0, v61
	v_exp_f32_e32 v61, v60
	v_mul_f32_e32 v60, 0xbfb8aa3b, v57
	v_exp_f32_e32 v62, v60
	v_rcp_f32_e32 v60, v59
	v_add_f32_e32 v59, 1.0, v61
	v_rcp_f32_e32 v58, v58
	v_add_f32_e32 v61, 1.0, v62
	v_rcp_f32_e32 v59, v59
	v_rcp_f32_e32 v61, v61
	v_mov_b32_e32 v62, v54
	v_mov_b32_e32 v63, v56
	v_mov_b32_e32 v56, v55
	v_pk_mul_f32 v[58:59], v[62:63], v[58:59]
	v_mov_b32_e32 v63, v52
	v_pk_mul_f32 v[54:55], v[56:57], v[60:61]
	v_mov_b32_e32 v52, v51
	v_mov_b32_e32 v62, v50
	v_pk_mul_f32 v[50:51], v[52:53], v[54:55]
	v_pk_mul_f32 v[58:59], v[62:63], v[58:59]
	v_and_b32_sdwa v54, v51, v177 dst_sel:DWORD dst_unused:UNUSED_PAD src0_sel:WORD_1 src1_sel:DWORD
	v_and_b32_sdwa v52, v59, v177 dst_sel:DWORD dst_unused:UNUSED_PAD src0_sel:WORD_1 src1_sel:DWORD
	v_and_b32_sdwa v55, v50, v177 dst_sel:DWORD dst_unused:UNUSED_PAD src0_sel:WORD_1 src1_sel:DWORD
	v_add3_u32 v51, v51, v54, s28
	v_and_b32_sdwa v53, v58, v177 dst_sel:DWORD dst_unused:UNUSED_PAD src0_sel:WORD_1 src1_sel:DWORD
	v_add3_u32 v52, v59, v52, s28
	v_add3_u32 v50, v50, v55, s28
	v_and_b32_e32 v51, 0xffff0000, v51
	v_add3_u32 v53, v58, v53, s28
	v_and_b32_e32 v50, 0xffff0000, v50
	v_or_b32_sdwa v51, v51, v52 dst_sel:DWORD dst_unused:UNUSED_PAD src0_sel:DWORD src1_sel:WORD_1
	v_mul_f32_e32 v52, 0xbfb8aa3b, v46
	v_or_b32_sdwa v50, v50, v53 dst_sel:DWORD dst_unused:UNUSED_PAD src0_sel:DWORD src1_sel:WORD_1
	v_exp_f32_e32 v52, v52
	v_mul_f32_e32 v53, 0xbfb8aa3b, v47
	v_exp_f32_e32 v53, v53
	global_store_dwordx2 v[66:67], v[50:51], off offset:32
	v_add_f32_e32 v50, 1.0, v52
	v_mul_f32_e32 v52, 0xbfb8aa3b, v48
	v_add_f32_e32 v51, 1.0, v53
	v_exp_f32_e32 v53, v52
	v_mul_f32_e32 v52, 0xbfb8aa3b, v49
	v_exp_f32_e32 v54, v52
	v_rcp_f32_e32 v52, v51
	v_add_f32_e32 v51, 1.0, v53
	v_rcp_f32_e32 v50, v50
	v_add_f32_e32 v53, 1.0, v54
	v_rcp_f32_e32 v51, v51
	v_rcp_f32_e32 v53, v53
	v_mov_b32_e32 v54, v46
	v_mov_b32_e32 v55, v48
	v_mov_b32_e32 v48, v47
	v_pk_mul_f32 v[50:51], v[54:55], v[50:51]
	v_mov_b32_e32 v55, v44
	v_pk_mul_f32 v[46:47], v[48:49], v[52:53]
	v_mov_b32_e32 v44, v43
	v_mov_b32_e32 v54, v42
	v_pk_mul_f32 v[42:43], v[44:45], v[46:47]
	v_pk_mul_f32 v[50:51], v[54:55], v[50:51]
	v_and_b32_sdwa v46, v43, v177 dst_sel:DWORD dst_unused:UNUSED_PAD src0_sel:WORD_1 src1_sel:DWORD
	v_and_b32_sdwa v44, v51, v177 dst_sel:DWORD dst_unused:UNUSED_PAD src0_sel:WORD_1 src1_sel:DWORD
	v_and_b32_sdwa v47, v42, v177 dst_sel:DWORD dst_unused:UNUSED_PAD src0_sel:WORD_1 src1_sel:DWORD
	v_add3_u32 v43, v43, v46, s28
	v_and_b32_sdwa v45, v50, v177 dst_sel:DWORD dst_unused:UNUSED_PAD src0_sel:WORD_1 src1_sel:DWORD
	v_add3_u32 v44, v51, v44, s28
	v_add3_u32 v42, v42, v47, s28
	v_and_b32_e32 v43, 0xffff0000, v43
	v_add3_u32 v45, v50, v45, s28
	v_and_b32_e32 v42, 0xffff0000, v42
	v_or_b32_sdwa v43, v43, v44 dst_sel:DWORD dst_unused:UNUSED_PAD src0_sel:DWORD src1_sel:WORD_1
	v_mul_f32_e32 v44, 0xbfb8aa3b, v38
	v_or_b32_sdwa v42, v42, v45 dst_sel:DWORD dst_unused:UNUSED_PAD src0_sel:DWORD src1_sel:WORD_1
	v_exp_f32_e32 v44, v44
	v_mul_f32_e32 v45, 0xbfb8aa3b, v39
	v_exp_f32_e32 v45, v45
	global_store_dwordx2 v[66:67], v[42:43], off offset:64
	v_add_f32_e32 v42, 1.0, v44
	v_mul_f32_e32 v44, 0xbfb8aa3b, v40
	v_add_f32_e32 v43, 1.0, v45
	v_exp_f32_e32 v45, v44
	v_mul_f32_e32 v44, 0xbfb8aa3b, v41
	v_exp_f32_e32 v46, v44
	v_rcp_f32_e32 v44, v43
	v_add_f32_e32 v43, 1.0, v45
	v_rcp_f32_e32 v42, v42
	v_add_f32_e32 v45, 1.0, v46
	v_rcp_f32_e32 v43, v43
	v_rcp_f32_e32 v45, v45
	v_mov_b32_e32 v46, v38
	v_mov_b32_e32 v47, v40
	v_mov_b32_e32 v40, v39
	v_pk_mul_f32 v[42:43], v[46:47], v[42:43]
	v_mov_b32_e32 v47, v36
	v_pk_mul_f32 v[38:39], v[40:41], v[44:45]
	v_mov_b32_e32 v36, v35
	v_mov_b32_e32 v46, v34
	v_pk_mul_f32 v[34:35], v[36:37], v[38:39]
	v_pk_mul_f32 v[42:43], v[46:47], v[42:43]
	v_and_b32_sdwa v38, v35, v177 dst_sel:DWORD dst_unused:UNUSED_PAD src0_sel:WORD_1 src1_sel:DWORD
	v_and_b32_sdwa v39, v34, v177 dst_sel:DWORD dst_unused:UNUSED_PAD src0_sel:WORD_1 src1_sel:DWORD
	v_and_b32_sdwa v36, v43, v177 dst_sel:DWORD dst_unused:UNUSED_PAD src0_sel:WORD_1 src1_sel:DWORD
	v_and_b32_sdwa v37, v42, v177 dst_sel:DWORD dst_unused:UNUSED_PAD src0_sel:WORD_1 src1_sel:DWORD
	v_add3_u32 v35, v35, v38, s28
	v_add3_u32 v34, v34, v39, s28
	v_add3_u32 v37, v42, v37, s28
	v_add3_u32 v36, v43, v36, s28
	v_and_b32_e32 v35, 0xffff0000, v35
	v_and_b32_e32 v34, 0xffff0000, v34
	v_or_b32_sdwa v35, v35, v36 dst_sel:DWORD dst_unused:UNUSED_PAD src0_sel:DWORD src1_sel:WORD_1
	v_or_b32_sdwa v34, v34, v37 dst_sel:DWORD dst_unused:UNUSED_PAD src0_sel:DWORD src1_sel:WORD_1
	global_store_dwordx2 v[66:67], v[34:35], off offset:96
	v_mul_f32_e32 v35, 0xbfb8aa3b, v30
	v_exp_f32_e32 v36, v35
	v_mul_f32_e32 v35, 0xbfb8aa3b, v31
	v_mul_f32_e32 v38, 0xbfb8aa3b, v32
	v_exp_f32_e32 v37, v35
	v_exp_f32_e32 v39, v38
	v_mul_f32_e32 v38, 0xbfb8aa3b, v33
	v_exp_f32_e32 v40, v38
	v_add_f32_e32 v37, 1.0, v37
	v_add_f32_e32 v36, 1.0, v36
	v_rcp_f32_e32 v38, v37
	v_add_f32_e32 v37, 1.0, v39
	v_add_f32_e32 v39, 1.0, v40
	v_rcp_f32_e32 v36, v36
	v_rcp_f32_e32 v37, v37
	v_rcp_f32_e32 v39, v39
	v_mov_b32_e32 v40, v30
	v_mov_b32_e32 v41, v32
	v_mov_b32_e32 v32, v31
	v_pk_mul_f32 v[36:37], v[40:41], v[36:37]
	v_mov_b32_e32 v41, v28
	v_pk_mul_f32 v[30:31], v[32:33], v[38:39]
	v_mov_b32_e32 v28, v27
	v_mov_b32_e32 v40, v26
	v_pk_mul_f32 v[26:27], v[28:29], v[30:31]
	v_pk_mul_f32 v[36:37], v[40:41], v[36:37]
	v_and_b32_sdwa v30, v27, v177 dst_sel:DWORD dst_unused:UNUSED_PAD src0_sel:WORD_1 src1_sel:DWORD
	v_and_b32_sdwa v28, v37, v177 dst_sel:DWORD dst_unused:UNUSED_PAD src0_sel:WORD_1 src1_sel:DWORD
	v_and_b32_sdwa v31, v26, v177 dst_sel:DWORD dst_unused:UNUSED_PAD src0_sel:WORD_1 src1_sel:DWORD
	v_add3_u32 v27, v27, v30, s28
	v_and_b32_sdwa v29, v36, v177 dst_sel:DWORD dst_unused:UNUSED_PAD src0_sel:WORD_1 src1_sel:DWORD
	v_add3_u32 v28, v37, v28, s28
	v_add3_u32 v26, v26, v31, s28
	v_and_b32_e32 v27, 0xffff0000, v27
	v_add3_u32 v29, v36, v29, s28
	v_and_b32_e32 v26, 0xffff0000, v26
	v_or_b32_sdwa v27, v27, v28 dst_sel:DWORD dst_unused:UNUSED_PAD src0_sel:DWORD src1_sel:WORD_1
	v_mul_f32_e32 v28, 0xbfb8aa3b, v22
	v_or_b32_sdwa v26, v26, v29 dst_sel:DWORD dst_unused:UNUSED_PAD src0_sel:DWORD src1_sel:WORD_1
	v_exp_f32_e32 v28, v28
	v_mul_f32_e32 v29, 0xbfb8aa3b, v23
	v_or_b32_e32 v34, 48, v110
	v_exp_f32_e32 v29, v29
	v_mad_i64_i32 v[34:35], s[6:7], v34, s52, v[106:107]
	v_lshl_add_u64 v[34:35], v[34:35], 0, v[108:109]
	global_store_dwordx2 v[34:35], v[26:27], off
	v_add_f32_e32 v26, 1.0, v28
	v_mul_f32_e32 v28, 0xbfb8aa3b, v24
	v_add_f32_e32 v27, 1.0, v29
	v_exp_f32_e32 v29, v28
	v_mul_f32_e32 v28, 0xbfb8aa3b, v25
	v_exp_f32_e32 v30, v28
	v_rcp_f32_e32 v28, v27
	v_add_f32_e32 v27, 1.0, v29
	v_rcp_f32_e32 v26, v26
	v_add_f32_e32 v29, 1.0, v30
	v_rcp_f32_e32 v27, v27
	v_rcp_f32_e32 v29, v29
	v_mov_b32_e32 v30, v22
	v_mov_b32_e32 v31, v24
	v_mov_b32_e32 v24, v23
	v_pk_mul_f32 v[26:27], v[30:31], v[26:27]
	v_mov_b32_e32 v31, v20
	v_pk_mul_f32 v[22:23], v[24:25], v[28:29]
	v_mov_b32_e32 v20, v19
	v_mov_b32_e32 v30, v18
	v_pk_mul_f32 v[18:19], v[20:21], v[22:23]
	v_pk_mul_f32 v[26:27], v[30:31], v[26:27]
	v_and_b32_sdwa v22, v19, v177 dst_sel:DWORD dst_unused:UNUSED_PAD src0_sel:WORD_1 src1_sel:DWORD
	v_and_b32_sdwa v20, v27, v177 dst_sel:DWORD dst_unused:UNUSED_PAD src0_sel:WORD_1 src1_sel:DWORD
	v_and_b32_sdwa v23, v18, v177 dst_sel:DWORD dst_unused:UNUSED_PAD src0_sel:WORD_1 src1_sel:DWORD
	v_add3_u32 v19, v19, v22, s28
	v_and_b32_sdwa v21, v26, v177 dst_sel:DWORD dst_unused:UNUSED_PAD src0_sel:WORD_1 src1_sel:DWORD
	v_add3_u32 v20, v27, v20, s28
	v_add3_u32 v18, v18, v23, s28
	v_and_b32_e32 v19, 0xffff0000, v19
	v_add3_u32 v21, v26, v21, s28
	v_and_b32_e32 v18, 0xffff0000, v18
	v_or_b32_sdwa v19, v19, v20 dst_sel:DWORD dst_unused:UNUSED_PAD src0_sel:DWORD src1_sel:WORD_1
	v_mul_f32_e32 v20, 0xbfb8aa3b, v14
	v_or_b32_sdwa v18, v18, v21 dst_sel:DWORD dst_unused:UNUSED_PAD src0_sel:DWORD src1_sel:WORD_1
	v_exp_f32_e32 v20, v20
	v_mul_f32_e32 v21, 0xbfb8aa3b, v15
	v_exp_f32_e32 v21, v21
	global_store_dwordx2 v[34:35], v[18:19], off offset:32
	v_add_f32_e32 v18, 1.0, v20
	v_mul_f32_e32 v20, 0xbfb8aa3b, v16
	v_add_f32_e32 v19, 1.0, v21
	v_exp_f32_e32 v21, v20
	v_mul_f32_e32 v20, 0xbfb8aa3b, v17
	v_exp_f32_e32 v22, v20
	v_rcp_f32_e32 v20, v19
	v_add_f32_e32 v19, 1.0, v21
	v_rcp_f32_e32 v18, v18
	v_add_f32_e32 v21, 1.0, v22
	v_rcp_f32_e32 v19, v19
	v_rcp_f32_e32 v21, v21
	v_mov_b32_e32 v22, v14
	v_mov_b32_e32 v23, v16
	v_mov_b32_e32 v16, v15
	v_pk_mul_f32 v[18:19], v[22:23], v[18:19]
	v_mov_b32_e32 v23, v12
	v_pk_mul_f32 v[14:15], v[16:17], v[20:21]
	v_mov_b32_e32 v12, v11
	v_mov_b32_e32 v22, v10
	v_pk_mul_f32 v[10:11], v[12:13], v[14:15]
	v_pk_mul_f32 v[18:19], v[22:23], v[18:19]
	v_and_b32_sdwa v14, v11, v177 dst_sel:DWORD dst_unused:UNUSED_PAD src0_sel:WORD_1 src1_sel:DWORD
	v_and_b32_sdwa v12, v19, v177 dst_sel:DWORD dst_unused:UNUSED_PAD src0_sel:WORD_1 src1_sel:DWORD
	v_and_b32_sdwa v15, v10, v177 dst_sel:DWORD dst_unused:UNUSED_PAD src0_sel:WORD_1 src1_sel:DWORD
	v_add3_u32 v11, v11, v14, s28
	v_and_b32_sdwa v13, v18, v177 dst_sel:DWORD dst_unused:UNUSED_PAD src0_sel:WORD_1 src1_sel:DWORD
	v_add3_u32 v12, v19, v12, s28
	v_add3_u32 v10, v10, v15, s28
	v_and_b32_e32 v11, 0xffff0000, v11
	v_add3_u32 v13, v18, v13, s28
	v_and_b32_e32 v10, 0xffff0000, v10
	v_or_b32_sdwa v11, v11, v12 dst_sel:DWORD dst_unused:UNUSED_PAD src0_sel:DWORD src1_sel:WORD_1
	v_mul_f32_e32 v12, 0xbfb8aa3b, v6
	v_or_b32_sdwa v10, v10, v13 dst_sel:DWORD dst_unused:UNUSED_PAD src0_sel:DWORD src1_sel:WORD_1
	v_exp_f32_e32 v12, v12
	v_mul_f32_e32 v13, 0xbfb8aa3b, v7
	v_exp_f32_e32 v13, v13
	global_store_dwordx2 v[34:35], v[10:11], off offset:64
	v_add_f32_e32 v10, 1.0, v12
	v_mul_f32_e32 v12, 0xbfb8aa3b, v8
	v_add_f32_e32 v11, 1.0, v13
	v_exp_f32_e32 v13, v12
	v_mul_f32_e32 v12, 0xbfb8aa3b, v9
	v_exp_f32_e32 v14, v12
	v_rcp_f32_e32 v12, v11
	v_add_f32_e32 v11, 1.0, v13
	v_rcp_f32_e32 v10, v10
	v_add_f32_e32 v13, 1.0, v14
	v_rcp_f32_e32 v11, v11
	v_rcp_f32_e32 v13, v13
	v_mov_b32_e32 v14, v6
	v_mov_b32_e32 v15, v8
	v_mov_b32_e32 v8, v7
	v_pk_mul_f32 v[10:11], v[14:15], v[10:11]
	v_mov_b32_e32 v15, v4
	v_pk_mul_f32 v[6:7], v[8:9], v[12:13]
	v_mov_b32_e32 v4, v3
	v_mov_b32_e32 v14, v2
	v_pk_mul_f32 v[2:3], v[4:5], v[6:7]
	v_pk_mul_f32 v[10:11], v[14:15], v[10:11]
	v_and_b32_sdwa v6, v3, v177 dst_sel:DWORD dst_unused:UNUSED_PAD src0_sel:WORD_1 src1_sel:DWORD
	v_and_b32_sdwa v7, v2, v177 dst_sel:DWORD dst_unused:UNUSED_PAD src0_sel:WORD_1 src1_sel:DWORD
	v_and_b32_sdwa v4, v11, v177 dst_sel:DWORD dst_unused:UNUSED_PAD src0_sel:WORD_1 src1_sel:DWORD
	v_and_b32_sdwa v5, v10, v177 dst_sel:DWORD dst_unused:UNUSED_PAD src0_sel:WORD_1 src1_sel:DWORD
	v_add3_u32 v3, v3, v6, s28
	v_add3_u32 v2, v2, v7, s28
	v_add3_u32 v5, v10, v5, s28
	v_add3_u32 v4, v11, v4, s28
	v_and_b32_e32 v3, 0xffff0000, v3
	v_and_b32_e32 v2, 0xffff0000, v2
	s_add_i32 s20, s20, s11
	v_or_b32_sdwa v3, v3, v4 dst_sel:DWORD dst_unused:UNUSED_PAD src0_sel:DWORD src1_sel:WORD_1
	v_or_b32_sdwa v2, v2, v5 dst_sel:DWORD dst_unused:UNUSED_PAD src0_sel:DWORD src1_sel:WORD_1
	s_cmpk_gt_i32 s20, 0x5ff
	global_store_dwordx2 v[34:35], v[2:3], off offset:96
	s_cbranch_scc0 .LBB0_465
